# weight conversions re-homed across GEMM tails: w_down to the out tail, w_up layer 1 split between merge and out tails of layer 1, w_in layer 1 split between up and down tails of layer 0
# speedup vs baseline: 1.0091x; 1.0091x over previous
; #define LAS __attribute__((address_space(3)))
; __device__ __forceinline__ int opaque_tid(int wv) { asm volatile("" : "+s"(wv)); unsigned z = 0u; asm volatile("" : "+v"(z)); const int l = __builtin_amdgcn_mbcnt_hi(~0u, __builtin_amdgcn_mbcnt_lo(~0u, z)); return (wv << 6) | l; }
; __device__ __forceinline__ void convert_weight(int wv, const float* __restrict__ src, int ldsrc, int Ksrc, bf16_t* dst, int ldd, int koff, int ntn, const float* kscale, int mode, LAS float* tile, int pidx, int pcnt) {
;     const int tid = opaque_tid(wv); const int ntk = Ksrc / 128; const int total = ntn * ntk; const int G = pcnt;
;     const int kk0 = tid >> 4, n4 = (tid & 15) * 4;
;     f32x4 v[4]; float ks[4];
;     auto prefetch = [&](int t) {
;         const int tn = t % ntn, tk = t / ntn; const int n0 = tn * 64, k0 = tk * 128;
;         int scol = n0, nvalid = 64;
;         if (mode == 1) { if (n0 < 5632) scol = n0; else if (n0 < 13312) scol = n0 + 8; else if (n0 == 13312) { scol = 5632; nvalid = 8; } else { scol = 0; nvalid = 0; } }
; #pragma unroll
;         for (int i = 0; i < 4; ++i) { const int kk = kk0 + i * 32; v[i] = (f32x4){0.f, 0.f, 0.f, 0.f};
;             if (n4 < nvalid) v[i] = *(const f32x4*)(src + (size_t)(k0 + kk) * ldsrc + scol + n4);
;             ks[i] = kscale ? kscale[k0 + kk] : 1.0f; }
;     };
;     int t = pidx; int buf = 0;
;     if (t < total) prefetch(t);
; __device__ __forceinline__ void convert_layer(int wv, PP P, int L, int mask, LAS float* tile, int pidx, int pcnt) {
;     ...
;     if (mask & 8) convert_weight(wv, P->w_up + (size_t)L * D * NUP, NUP, D, (bf16_t*)(dob + DO_WUP), D, 0, NUP / 64, P->norm_ffn + L * D, 0, tile, pidx, pcnt);
.LBB0_554:
	s_mov_b32 s8, s95
	s_waitcnt vmcnt(0)
	v_mov_b32_e32 v0, v3
	s_cmpk_gt_i32 s20, 0x57f
	s_cbranch_scc1 .LBB0_561
	s_cmp_eq_u32 s2, 0
	s_cbranch_scc1 .LBB0_561
	v_mbcnt_lo_u32_b32 v10, -1, 0
	v_mbcnt_hi_u32_b32 v10, -1, v10
	v_lshl_or_b32 v10, s95, 6, v10
	v_lshrrev_b32_e32 v11, 4, v10
	v_and_b32_e32 v9, 15, v10
	v_lshlrev_b32_e32 v9, 2, v9
	v_mul_u32_u24_e32 v4, 0x2c00, v11
	v_add_u32_e32 v4, v4, v9
	v_lshlrev_b32_e32 v4, 2, v4
	v_lshlrev_b32_e32 v5, 2, v11
	v_mul_u32_u24_e32 v6, 65, v11
	v_add_u32_e32 v6, v6, v9
	v_lshlrev_b32_e32 v6, 2, v6
	v_lshrrev_b32_e32 v7, 3, v10
	v_and_b32_e32 v8, 7, v10
	v_lshlrev_b32_e32 v8, 4, v8
	v_mul_u32_u24_e32 v11, 65, v8
	v_add_u32_e32 v11, v11, v7
	v_lshlrev_b32_e32 v8, 1, v8
	v_mul_u32_u24_e32 v10, 0x1000, v7
	v_add_u32_e32 v8, v10, v8
	v_lshlrev_b32_e32 v7, 2, v11
	s_load_dwordx2 s[4:5], s[0:1], 0x70
	s_load_dwordx2 s[6:7], s[0:1], 0x68
	s_load_dwordx2 s[8:9], s[0:1], 0x98
	s_waitcnt lgkmcnt(0)
	s_add_u32 s4, s4, 0x5800000
	s_addc_u32 s5, s5, 0
	s_add_u32 s6, s6, 0x2000
	s_addc_u32 s7, s7, 0
	s_add_u32 s8, s8, 0x5200000
	s_addc_u32 s9, s9, 0
	s_sub_u32 s10, s81, 64
	s_mul_hi_u32 s15, s10, 0x1745d18
	s_mul_i32 s14, s15, 176
	s_sub_u32 s14, s10, s14
	s_lshl_b32 s18, s14, 6
	s_mov_b32 s28, 0
	s_mul_i32 s19, s15, 0x160000
	s_add_u32 s19, s19, s18
	s_lshl_b32 s19, s19, 2
	s_add_u32 s20, s4, s19
	s_addc_u32 s21, s5, 0
	s_lshl_b32 s19, s15, 9
	s_add_u32 s22, s6, s19
	s_addc_u32 s23, s7, 0
	global_load_dwordx4 v[12:15], v4, s[20:21]
	global_load_dword v28, v5, s[22:23]
	s_add_u32 s20, s20, 0x160000
	s_addc_u32 s21, s21, 0
	global_load_dwordx4 v[16:19], v4, s[20:21]
	global_load_dword v29, v5, s[22:23] offset:128
	s_add_u32 s20, s20, 0x160000
	s_addc_u32 s21, s21, 0
	global_load_dwordx4 v[20:23], v4, s[20:21]
	global_load_dword v30, v5, s[22:23] offset:256
	s_add_u32 s20, s20, 0x160000
	s_addc_u32 s21, s21, 0
	global_load_dwordx4 v[24:27], v4, s[20:21]
	global_load_dword v31, v5, s[22:23] offset:384
	s_add_u32 s11, s10, 192
	s_cmp_lt_u32 s11, 2304
	s_cbranch_scc0 .Lcv4_p1n
	s_mul_hi_u32 s15, s11, 0x1745d18
	s_mul_i32 s14, s15, 176
	s_sub_u32 s14, s11, s14
	s_lshl_b32 s18, s14, 6
	s_mov_b32 s29, 0
	s_mul_i32 s19, s15, 0x160000
	s_add_u32 s19, s19, s18
	s_lshl_b32 s19, s19, 2
	s_add_u32 s20, s4, s19
	s_addc_u32 s21, s5, 0
	s_lshl_b32 s19, s15, 9
	s_add_u32 s22, s6, s19
	s_addc_u32 s23, s7, 0
	global_load_dwordx4 v[32:35], v4, s[20:21]
	global_load_dword v48, v5, s[22:23]
	s_add_u32 s20, s20, 0x160000
	s_addc_u32 s21, s21, 0
	global_load_dwordx4 v[36:39], v4, s[20:21]
	global_load_dword v49, v5, s[22:23] offset:128
	s_add_u32 s20, s20, 0x160000
	s_addc_u32 s21, s21, 0
	global_load_dwordx4 v[40:43], v4, s[20:21]
	global_load_dword v50, v5, s[22:23] offset:256
	s_add_u32 s20, s20, 0x160000
	s_addc_u32 s21, s21, 0
	global_load_dwordx4 v[44:47], v4, s[20:21]
	global_load_dword v51, v5, s[22:23] offset:384
	s_waitcnt vmcnt(8)
	s_branch .Lcv4_loop

; #define LAS __attribute__((address_space(3)))
; __device__ __forceinline__ void lds_barrier() { asm volatile("s_waitcnt lgkmcnt(0)" ::: "memory"); __builtin_amdgcn_s_barrier(); asm volatile("" ::: "memory"); }
; __device__ __forceinline__ void convert_weight(int wv, const float* __restrict__ src, int ldsrc, int Ksrc, bf16_t* dst, int ldd, int koff, int ntn, const float* kscale, int mode, LAS float* tile, int pidx, int pcnt) {
;     ...
;     auto prefetch = [&](int t) {
;         const int tn = t % ntn, tk = t / ntn; const int n0 = tn * 64, k0 = tk * 128;
;         int scol = n0, nvalid = 64;
;         if (mode == 1) { if (n0 < 5632) scol = n0; else if (n0 < 13312) scol = n0 + 8; else if (n0 == 13312) { scol = 5632; nvalid = 8; } else { scol = 0; nvalid = 0; } }
; #pragma unroll
;         for (int i = 0; i < 4; ++i) { const int kk = kk0 + i * 32; v[i] = (f32x4){0.f, 0.f, 0.f, 0.f};
;             if (n4 < nvalid) v[i] = *(const f32x4*)(src + (size_t)(k0 + kk) * ldsrc + scol + n4);
;             ks[i] = kscale ? kscale[k0 + kk] : 1.0f; }
;     };
;     int t = pidx; int buf = 0;
;     if (t < total) prefetch(t);
;     for (; t < total; t += G) {
;         LAS float* tl = tile + buf * (128 * 65);
; #pragma unroll
;         for (int i = 0; i < 4; ++i) { const int kk = kk0 + i * 32;
;             tl[kk * 65 + n4 + 0] = v[i][0] * ks[i]; tl[kk * 65 + n4 + 1] = v[i][1] * ks[i]; tl[kk * 65 + n4 + 2] = v[i][2] * ks[i]; tl[kk * 65 + n4 + 3] = v[i][3] * ks[i]; }
;         lds_barrier();
;         const int tn = t % ntn, tk = t / ntn; const int n0 = tn * 64, k0 = tk * 128;
;         if (t + G < total) prefetch(t + G);
;         { const int n = tid >> 3, k16 = (tid & 7) * 16; u32x4 w0, w1;
;           w0.x = pack2(tl[(k16 + 0) * 65 + n], tl[(k16 + 1) * 65 + n]); w0.y = pack2(tl[(k16 + 2) * 65 + n], tl[(k16 + 3) * 65 + n]);
;           w0.z = pack2(tl[(k16 + 4) * 65 + n], tl[(k16 + 5) * 65 + n]); w0.w = pack2(tl[(k16 + 6) * 65 + n], tl[(k16 + 7) * 65 + n]);
;           w1.x = pack2(tl[(k16 + 8) * 65 + n], tl[(k16 + 9) * 65 + n]); w1.y = pack2(tl[(k16 + 10) * 65 + n], tl[(k16 + 11) * 65 + n]);
;           w1.z = pack2(tl[(k16 + 12) * 65 + n], tl[(k16 + 13) * 65 + n]); w1.w = pack2(tl[(k16 + 14) * 65 + n], tl[(k16 + 15) * 65 + n]);
;           bf16_t* dp = dst + (size_t)(n0 + n) * ldd + koff + k0 + k16; *(u32x4*)dp = w0; *(u32x4*)(dp + 8) = w1; }
;         buf ^= 1;
.Lcv4_loop:
	v_mul_f32_e32 v12, v12, v28
	v_mul_f32_e32 v13, v13, v28
	v_mul_f32_e32 v14, v14, v28
	v_mul_f32_e32 v15, v15, v28
	v_mul_f32_e32 v16, v16, v29
	v_mul_f32_e32 v17, v17, v29
	v_mul_f32_e32 v18, v18, v29
	v_mul_f32_e32 v19, v19, v29
	v_mul_f32_e32 v20, v20, v30
	v_mul_f32_e32 v21, v21, v30
	v_mul_f32_e32 v22, v22, v30
	v_mul_f32_e32 v23, v23, v30
	v_mul_f32_e32 v24, v24, v31
	v_mul_f32_e32 v25, v25, v31
	v_mul_f32_e32 v26, v26, v31
	v_mul_f32_e32 v27, v27, v31
	ds_write_b32 v6, v12 offset:0
	ds_write_b32 v6, v13 offset:4
	ds_write_b32 v6, v14 offset:8
	ds_write_b32 v6, v15 offset:12
	ds_write_b32 v6, v16 offset:8320
	ds_write_b32 v6, v17 offset:8324
	ds_write_b32 v6, v18 offset:8328
	ds_write_b32 v6, v19 offset:8332
	ds_write_b32 v6, v20 offset:16640
	ds_write_b32 v6, v21 offset:16644
	ds_write_b32 v6, v22 offset:16648
	ds_write_b32 v6, v23 offset:16652
	ds_write_b32 v6, v24 offset:24960
	ds_write_b32 v6, v25 offset:24964
	ds_write_b32 v6, v26 offset:24968
	ds_write_b32 v6, v27 offset:24972
	s_waitcnt lgkmcnt(0)
	s_barrier
	s_add_u32 s11, s10, 384
	s_mov_b32 s27, 0
	s_cmp_lt_u32 s11, 2304
	s_cbranch_scc0 .Lcv4_na
	s_mov_b32 s27, 1
	s_mul_hi_u32 s15, s11, 0x1745d18
	s_mul_i32 s14, s15, 176
	s_sub_u32 s14, s11, s14
	s_lshl_b32 s18, s14, 6
	s_mov_b32 s28, 0
	s_mul_i32 s19, s15, 0x160000
	s_add_u32 s19, s19, s18
	s_lshl_b32 s19, s19, 2
	s_add_u32 s20, s4, s19
	s_addc_u32 s21, s5, 0
	s_lshl_b32 s19, s15, 9
	s_add_u32 s22, s6, s19
	s_addc_u32 s23, s7, 0
	global_load_dwordx4 v[12:15], v4, s[20:21]
	global_load_dword v28, v5, s[22:23]
	s_add_u32 s20, s20, 0x160000
	s_addc_u32 s21, s21, 0
	global_load_dwordx4 v[16:19], v4, s[20:21]
	global_load_dword v29, v5, s[22:23] offset:128
	s_add_u32 s20, s20, 0x160000
	s_addc_u32 s21, s21, 0
	global_load_dwordx4 v[20:23], v4, s[20:21]
	global_load_dword v30, v5, s[22:23] offset:256
	s_add_u32 s20, s20, 0x160000
	s_addc_u32 s21, s21, 0
	global_load_dwordx4 v[24:27], v4, s[20:21]
	global_load_dword v31, v5, s[22:23] offset:384
.Lcv4_na:
	ds_read_b32 v52, v7 offset:0
	ds_read_b32 v53, v7 offset:260
	ds_read_b32 v54, v7 offset:520
	ds_read_b32 v55, v7 offset:780
	ds_read_b32 v56, v7 offset:1040
	ds_read_b32 v57, v7 offset:1300
	ds_read_b32 v58, v7 offset:1560
	ds_read_b32 v59, v7 offset:1820
	ds_read_b32 v60, v7 offset:2080
	ds_read_b32 v61, v7 offset:2340
	ds_read_b32 v62, v7 offset:2600
	ds_read_b32 v63, v7 offset:2860
	ds_read_b32 v64, v7 offset:3120
	ds_read_b32 v65, v7 offset:3380
	ds_read_b32 v66, v7 offset:3640
	ds_read_b32 v67, v7 offset:3900
	s_mul_hi_u32 s15, s10, 0x1745d18
	s_mul_i32 s14, s15, 176
	s_sub_u32 s14, s10, s14
	s_mul_i32 s14, s14, 0x40000
	s_lshl_b32 s15, s15, 8
	s_add_u32 s14, s14, s15
	s_add_u32 s24, s8, s14
	s_addc_u32 s25, s9, 0
	s_waitcnt lgkmcnt(14)
	v_cvt_pk_bf16_f32 v68, v52, v53
	s_waitcnt lgkmcnt(12)
	v_cvt_pk_bf16_f32 v69, v54, v55
	s_waitcnt lgkmcnt(10)
	v_cvt_pk_bf16_f32 v70, v56, v57
	s_waitcnt lgkmcnt(8)
	v_cvt_pk_bf16_f32 v71, v58, v59
	s_waitcnt lgkmcnt(6)
	v_cvt_pk_bf16_f32 v72, v60, v61
	s_waitcnt lgkmcnt(4)
	v_cvt_pk_bf16_f32 v73, v62, v63
	s_waitcnt lgkmcnt(2)
	v_cvt_pk_bf16_f32 v74, v64, v65
	s_waitcnt lgkmcnt(0)
	v_cvt_pk_bf16_f32 v75, v66, v67
	global_store_dwordx4 v8, v[68:71], s[24:25]
	global_store_dwordx4 v8, v[72:75], s[24:25] offset:16
	s_add_u32 s10, s10, 192
	s_cmp_lt_u32 s10, 2304
	s_cbranch_scc0 .Lcv4_end
	s_cmp_eq_u32 s27, 0
	s_cbranch_scc1 .Lcv4_wa
	s_waitcnt vmcnt(10)
	s_branch .Lcv4_xa

; #define LAS __attribute__((address_space(3)))
; __device__ __forceinline__ void lds_barrier() { asm volatile("s_waitcnt lgkmcnt(0)" ::: "memory"); __builtin_amdgcn_s_barrier(); asm volatile("" ::: "memory"); }
; __device__ __forceinline__ void convert_weight(int wv, const float* __restrict__ src, int ldsrc, int Ksrc, bf16_t* dst, int ldd, int koff, int ntn, const float* kscale, int mode, LAS float* tile, int pidx, int pcnt) {
;     ...
;     auto prefetch = [&](int t) {
;         const int tn = t % ntn, tk = t / ntn; const int n0 = tn * 64, k0 = tk * 128;
;         int scol = n0, nvalid = 64;
;         if (mode == 1) { if (n0 < 5632) scol = n0; else if (n0 < 13312) scol = n0 + 8; else if (n0 == 13312) { scol = 5632; nvalid = 8; } else { scol = 0; nvalid = 0; } }
; #pragma unroll
;         for (int i = 0; i < 4; ++i) { const int kk = kk0 + i * 32; v[i] = (f32x4){0.f, 0.f, 0.f, 0.f};
;             if (n4 < nvalid) v[i] = *(const f32x4*)(src + (size_t)(k0 + kk) * ldsrc + scol + n4);
;             ks[i] = kscale ? kscale[k0 + kk] : 1.0f; }
;     };
;     int t = pidx; int buf = 0;
;     if (t < total) prefetch(t);
;     for (; t < total; t += G) {
;         LAS float* tl = tile + buf * (128 * 65);
; #pragma unroll
;         for (int i = 0; i < 4; ++i) { const int kk = kk0 + i * 32;
;             tl[kk * 65 + n4 + 0] = v[i][0] * ks[i]; tl[kk * 65 + n4 + 1] = v[i][1] * ks[i]; tl[kk * 65 + n4 + 2] = v[i][2] * ks[i]; tl[kk * 65 + n4 + 3] = v[i][3] * ks[i]; }
;         lds_barrier();
;         const int tn = t % ntn, tk = t / ntn; const int n0 = tn * 64, k0 = tk * 128;
;         if (t + G < total) prefetch(t + G);
;         { const int n = tid >> 3, k16 = (tid & 7) * 16; u32x4 w0, w1;
;           w0.x = pack2(tl[(k16 + 0) * 65 + n], tl[(k16 + 1) * 65 + n]); w0.y = pack2(tl[(k16 + 2) * 65 + n], tl[(k16 + 3) * 65 + n]);
;           w0.z = pack2(tl[(k16 + 4) * 65 + n], tl[(k16 + 5) * 65 + n]); w0.w = pack2(tl[(k16 + 6) * 65 + n], tl[(k16 + 7) * 65 + n]);
;           w1.x = pack2(tl[(k16 + 8) * 65 + n], tl[(k16 + 9) * 65 + n]); w1.y = pack2(tl[(k16 + 10) * 65 + n], tl[(k16 + 11) * 65 + n]);
;           w1.z = pack2(tl[(k16 + 12) * 65 + n], tl[(k16 + 13) * 65 + n]); w1.w = pack2(tl[(k16 + 14) * 65 + n], tl[(k16 + 15) * 65 + n]);
;           bf16_t* dp = dst + (size_t)(n0 + n) * ldd + koff + k0 + k16; *(u32x4*)dp = w0; *(u32x4*)(dp + 8) = w1; }
;         buf ^= 1;
.Lcv4_xa:
	v_mul_f32_e32 v32, v32, v48
	v_mul_f32_e32 v33, v33, v48
	v_mul_f32_e32 v34, v34, v48
	v_mul_f32_e32 v35, v35, v48
	v_mul_f32_e32 v36, v36, v49
	v_mul_f32_e32 v37, v37, v49
	v_mul_f32_e32 v38, v38, v49
	v_mul_f32_e32 v39, v39, v49
	v_mul_f32_e32 v40, v40, v50
	v_mul_f32_e32 v41, v41, v50
	v_mul_f32_e32 v42, v42, v50
	v_mul_f32_e32 v43, v43, v50
	v_mul_f32_e32 v44, v44, v51
	v_mul_f32_e32 v45, v45, v51
	v_mul_f32_e32 v46, v46, v51
	v_mul_f32_e32 v47, v47, v51
	ds_write_b32 v6, v32 offset:33280
	ds_write_b32 v6, v33 offset:33284
	ds_write_b32 v6, v34 offset:33288
	ds_write_b32 v6, v35 offset:33292
	ds_write_b32 v6, v36 offset:41600
	ds_write_b32 v6, v37 offset:41604
	ds_write_b32 v6, v38 offset:41608
	ds_write_b32 v6, v39 offset:41612
	ds_write_b32 v6, v40 offset:49920
	ds_write_b32 v6, v41 offset:49924
	ds_write_b32 v6, v42 offset:49928
	ds_write_b32 v6, v43 offset:49932
	ds_write_b32 v6, v44 offset:58240
	ds_write_b32 v6, v45 offset:58244
	ds_write_b32 v6, v46 offset:58248
	ds_write_b32 v6, v47 offset:58252
	s_waitcnt lgkmcnt(0)
	s_barrier
	s_add_u32 s11, s10, 384
	s_mov_b32 s27, 0
	s_cmp_lt_u32 s11, 2304
	s_cbranch_scc0 .Lcv4_nb
	s_mov_b32 s27, 1
	s_mul_hi_u32 s15, s11, 0x1745d18
	s_mul_i32 s14, s15, 176
	s_sub_u32 s14, s11, s14
	s_lshl_b32 s18, s14, 6
	s_mov_b32 s29, 0
	s_mul_i32 s19, s15, 0x160000
	s_add_u32 s19, s19, s18
	s_lshl_b32 s19, s19, 2
	s_add_u32 s20, s4, s19
	s_addc_u32 s21, s5, 0
	s_lshl_b32 s19, s15, 9
	s_add_u32 s22, s6, s19
	s_addc_u32 s23, s7, 0
	global_load_dwordx4 v[32:35], v4, s[20:21]
	global_load_dword v48, v5, s[22:23]
	s_add_u32 s20, s20, 0x160000
	s_addc_u32 s21, s21, 0
	global_load_dwordx4 v[36:39], v4, s[20:21]
	global_load_dword v49, v5, s[22:23] offset:128
	s_add_u32 s20, s20, 0x160000
	s_addc_u32 s21, s21, 0
	global_load_dwordx4 v[40:43], v4, s[20:21]
	global_load_dword v50, v5, s[22:23] offset:256
	s_add_u32 s20, s20, 0x160000
	s_addc_u32 s21, s21, 0
	global_load_dwordx4 v[44:47], v4, s[20:21]
	global_load_dword v51, v5, s[22:23] offset:384
.Lcv4_nb:
	ds_read_b32 v52, v7 offset:33280
	ds_read_b32 v53, v7 offset:33540
	ds_read_b32 v54, v7 offset:33800
	ds_read_b32 v55, v7 offset:34060
	ds_read_b32 v56, v7 offset:34320
	ds_read_b32 v57, v7 offset:34580
	ds_read_b32 v58, v7 offset:34840
	ds_read_b32 v59, v7 offset:35100
	ds_read_b32 v60, v7 offset:35360
	ds_read_b32 v61, v7 offset:35620
	ds_read_b32 v62, v7 offset:35880
	ds_read_b32 v63, v7 offset:36140
	ds_read_b32 v64, v7 offset:36400
	ds_read_b32 v65, v7 offset:36660
	ds_read_b32 v66, v7 offset:36920
	ds_read_b32 v67, v7 offset:37180
	s_mul_hi_u32 s15, s10, 0x1745d18
	s_mul_i32 s14, s15, 176
	s_sub_u32 s14, s10, s14
	s_mul_i32 s14, s14, 0x40000
	s_lshl_b32 s15, s15, 8
	s_add_u32 s14, s14, s15
	s_add_u32 s24, s8, s14
	s_addc_u32 s25, s9, 0
	s_waitcnt lgkmcnt(14)
	v_cvt_pk_bf16_f32 v68, v52, v53
	s_waitcnt lgkmcnt(12)
	v_cvt_pk_bf16_f32 v69, v54, v55
	s_waitcnt lgkmcnt(10)
	v_cvt_pk_bf16_f32 v70, v56, v57
	s_waitcnt lgkmcnt(8)
	v_cvt_pk_bf16_f32 v71, v58, v59
	s_waitcnt lgkmcnt(6)
	v_cvt_pk_bf16_f32 v72, v60, v61
	s_waitcnt lgkmcnt(4)
	v_cvt_pk_bf16_f32 v73, v62, v63
	s_waitcnt lgkmcnt(2)
	v_cvt_pk_bf16_f32 v74, v64, v65
	s_waitcnt lgkmcnt(0)
	v_cvt_pk_bf16_f32 v75, v66, v67
	global_store_dwordx4 v8, v[68:71], s[24:25]
	global_store_dwordx4 v8, v[72:75], s[24:25] offset:16
	s_add_u32 s10, s10, 192
	s_cmp_lt_u32 s10, 2304
	s_cbranch_scc0 .Lcv4_end
	s_cmp_eq_u32 s27, 0
	s_cbranch_scc1 .Lcv4_wb
	s_waitcnt vmcnt(10)
	s_branch .Lcv4_xb

; #define LAS __attribute__((address_space(3)))
; __device__ __forceinline__ int opaque_tid(int wv) { asm volatile("" : "+s"(wv)); unsigned z = 0u; asm volatile("" : "+v"(z)); const int l = __builtin_amdgcn_mbcnt_hi(~0u, __builtin_amdgcn_mbcnt_lo(~0u, z)); return (wv << 6) | l; }
; __device__ __forceinline__ void convert_weight(int wv, const float* __restrict__ src, int ldsrc, int Ksrc, bf16_t* dst, int ldd, int koff, int ntn, const float* kscale, int mode, LAS float* tile, int pidx, int pcnt) {
;     const int tid = opaque_tid(wv); const int ntk = Ksrc / 128; const int total = ntn * ntk; const int G = pcnt;
;     const int kk0 = tid >> 4, n4 = (tid & 15) * 4;
;     f32x4 v[4]; float ks[4];
;     auto prefetch = [&](int t) {
;         const int tn = t % ntn, tk = t / ntn; const int n0 = tn * 64, k0 = tk * 128;
;         int scol = n0, nvalid = 64;
;         if (mode == 1) { if (n0 < 5632) scol = n0; else if (n0 < 13312) scol = n0 + 8; else if (n0 == 13312) { scol = 5632; nvalid = 8; } else { scol = 0; nvalid = 0; } }
; #pragma unroll
;         for (int i = 0; i < 4; ++i) { const int kk = kk0 + i * 32; v[i] = (f32x4){0.f, 0.f, 0.f, 0.f};
;             if (n4 < nvalid) v[i] = *(const f32x4*)(src + (size_t)(k0 + kk) * ldsrc + scol + n4);
;             ks[i] = kscale ? kscale[k0 + kk] : 1.0f; }
;     };
;     int t = pidx; int buf = 0;
;     if (t < total) prefetch(t);
; __device__ __forceinline__ void convert_layer(int wv, PP P, int L, int mask, LAS float* tile, int pidx, int pcnt) {
;     ...
;     if (mask & 16) convert_weight(wv, P->w_down + (size_t)L * DFF * D, D, DFF, (bf16_t*)(ws + WS_WDOWN), DFF, 0, D / 64, nullptr, 0, tile, pidx, pcnt);
.LBB0_642:
	v_readlane_b32 s4, v254, 30
	v_readlane_b32 s5, v254, 31
	s_and_b64 vcc, exec, s[4:5]
	s_mov_b32 s4, s81
	s_movk_i32 s5, 64
	s_cmp_lt_i32 s4, s5
	s_cselect_b64 s[6:7], -1, 0
	s_or_b64 s[6:7], s[82:83], s[6:7]
	s_and_b64 vcc, exec, s[6:7]
	s_cbranch_vccnz .LBB0_703
	s_movk_i32 s5, 64
	s_sub_i32 s22, s4, s5
	s_mov_b64 s[10:11], s[0:1]
	s_mov_b32 s8, s95
	v_mov_b32_e32 v0, v3
	s_cmpk_gt_i32 s22, 0xd3f
	s_cbranch_scc1 .LBB0_702
	v_mbcnt_lo_u32_b32 v10, -1, 0
	v_mbcnt_hi_u32_b32 v10, -1, v10
	v_lshl_or_b32 v10, s95, 6, v10
	v_lshrrev_b32_e32 v11, 4, v10
	v_and_b32_e32 v9, 15, v10
	v_lshlrev_b32_e32 v9, 2, v9
	v_mul_u32_u24_e32 v4, 0x800, v11
	v_add_u32_e32 v4, v4, v9
	v_lshlrev_b32_e32 v4, 2, v4
	v_lshlrev_b32_e32 v5, 2, v11
	v_mul_u32_u24_e32 v6, 65, v11
	v_add_u32_e32 v6, v6, v9
	v_lshlrev_b32_e32 v6, 2, v6
	v_lshrrev_b32_e32 v7, 3, v10
	v_and_b32_e32 v8, 7, v10
	v_lshlrev_b32_e32 v8, 4, v8
	v_mul_u32_u24_e32 v11, 65, v8
	v_add_u32_e32 v11, v11, v7
	v_lshlrev_b32_e32 v8, 1, v8
	v_mul_u32_u24_e32 v10, 0x2c00, v7
	v_add_u32_e32 v8, v10, v8
	v_lshlrev_b32_e32 v7, 2, v11
	s_load_dwordx2 s[4:5], s[0:1], 0x88
	s_load_dwordx2 s[8:9], s[0:1], 0xa0
	s_waitcnt lgkmcnt(0)
	s_mul_i32 s19, s2, 0x2c00000
	s_add_u32 s4, s4, s19
	s_addc_u32 s5, s5, 0
	s_add_u32 s8, s8, 0x26600000
	s_addc_u32 s9, s9, 0
	s_mov_b32 s10, s22
	s_mul_hi_u32 s15, s10, 0x8000000
	s_mul_i32 s14, s15, 32
	s_sub_u32 s14, s10, s14
	s_lshl_b32 s18, s14, 6
	s_mov_b32 s28, 0
	s_mul_i32 s19, s15, 0x40000
	s_add_u32 s19, s19, s18
	s_lshl_b32 s19, s19, 2
	s_add_u32 s20, s4, s19
	s_addc_u32 s21, s5, 0
	global_load_dwordx4 v[12:15], v4, s[20:21]
	s_add_u32 s20, s20, 0x40000
	s_addc_u32 s21, s21, 0
	global_load_dwordx4 v[16:19], v4, s[20:21]
	s_add_u32 s20, s20, 0x40000
	s_addc_u32 s21, s21, 0
	global_load_dwordx4 v[20:23], v4, s[20:21]
	s_add_u32 s20, s20, 0x40000
	s_addc_u32 s21, s21, 0
	global_load_dwordx4 v[24:27], v4, s[20:21]
	s_add_u32 s11, s10, 192
	s_cmp_lt_u32 s11, 1408
	s_cbranch_scc0 .Lcv6_p1n
	s_mul_hi_u32 s15, s11, 0x8000000
	s_mul_i32 s14, s15, 32
	s_sub_u32 s14, s11, s14
	s_lshl_b32 s18, s14, 6
	s_mov_b32 s29, 0
	s_mul_i32 s19, s15, 0x40000
	s_add_u32 s19, s19, s18
	s_lshl_b32 s19, s19, 2
	s_add_u32 s20, s4, s19
	s_addc_u32 s21, s5, 0
	global_load_dwordx4 v[32:35], v4, s[20:21]
	s_add_u32 s20, s20, 0x40000
	s_addc_u32 s21, s21, 0
	global_load_dwordx4 v[36:39], v4, s[20:21]
	s_add_u32 s20, s20, 0x40000
	s_addc_u32 s21, s21, 0
	global_load_dwordx4 v[40:43], v4, s[20:21]
	s_add_u32 s20, s20, 0x40000
	s_addc_u32 s21, s21, 0
	global_load_dwordx4 v[44:47], v4, s[20:21]
	s_waitcnt vmcnt(4)
	s_branch .Lcv6_loop

; __device__ __forceinline__ int opaque_tid(int wv) { asm volatile("" : "+s"(wv)); unsigned z = 0u; asm volatile("" : "+v"(z)); const int l = __builtin_amdgcn_mbcnt_hi(~0u, __builtin_amdgcn_mbcnt_lo(~0u, z)); return (wv << 6) | l; }
; __device__ __forceinline__ void convert_weight(int wv, const float* __restrict__ src, int ldsrc, int Ksrc, bf16_t* dst, int ldd, int koff, int ntn, const float* kscale, int mode, LAS float* tile, int pidx, int pcnt) {
;     const int tid = opaque_tid(wv); const int ntk = Ksrc / 128; const int total = ntn * ntk; const int G = pcnt;
;     const int kk0 = tid >> 4, n4 = (tid & 15) * 4;
;     f32x4 v[4]; float ks[4];
;     auto prefetch = [&](int t) {
;         const int tn = t % ntn, tk = t / ntn; const int n0 = tn * 64, k0 = tk * 128;
;         int scol = n0, nvalid = 64;
;         if (mode == 1) { if (n0 < 5632) scol = n0; else if (n0 < 13312) scol = n0 + 8; else if (n0 == 13312) { scol = 5632; nvalid = 8; } else { scol = 0; nvalid = 0; } }
; #pragma unroll
;         for (int i = 0; i < 4; ++i) { const int kk = kk0 + i * 32; v[i] = (f32x4){0.f, 0.f, 0.f, 0.f};
;             if (n4 < nvalid) v[i] = *(const f32x4*)(src + (size_t)(k0 + kk) * ldsrc + scol + n4);
;             ks[i] = kscale ? kscale[k0 + kk] : 1.0f; }
;     };
;     int t = pidx; int buf = 0;
;     if (t < total) prefetch(t);
; __device__ __forceinline__ void convert_layer(int wv, PP P, int L, int mask, LAS float* tile, int pidx, int pcnt) {
;     ...
;     if (mask & 8) convert_weight(wv, P->w_up + (size_t)L * D * NUP, NUP, D, (bf16_t*)(dob + DO_WUP), D, 0, NUP / 64, P->norm_ffn + L * D, 0, tile, pidx, pcnt);
.Lcv6_end:
	s_cmp_eq_u32 s2, 0
	s_cbranch_scc1 .LBB0_702
	s_waitcnt lgkmcnt(0)
	s_barrier
	v_mbcnt_lo_u32_b32 v10, -1, 0
	v_mbcnt_hi_u32_b32 v10, -1, v10
	v_lshl_or_b32 v10, s95, 6, v10
	v_lshrrev_b32_e32 v11, 4, v10
	v_and_b32_e32 v9, 15, v10
	v_lshlrev_b32_e32 v9, 2, v9
	v_mul_u32_u24_e32 v4, 0x2c00, v11
	v_add_u32_e32 v4, v4, v9
	v_lshlrev_b32_e32 v4, 2, v4
	v_lshlrev_b32_e32 v5, 2, v11
	v_mul_u32_u24_e32 v6, 65, v11
	v_add_u32_e32 v6, v6, v9
	v_lshlrev_b32_e32 v6, 2, v6
	v_lshrrev_b32_e32 v7, 3, v10
	v_and_b32_e32 v8, 7, v10
	v_lshlrev_b32_e32 v8, 4, v8
	v_mul_u32_u24_e32 v11, 65, v8
	v_add_u32_e32 v11, v11, v7
	v_lshlrev_b32_e32 v8, 1, v8
	v_mul_u32_u24_e32 v10, 0x1000, v7
	v_add_u32_e32 v8, v10, v8
	v_lshlrev_b32_e32 v7, 2, v11
	s_load_dwordx2 s[4:5], s[0:1], 0x70
	s_load_dwordx2 s[6:7], s[0:1], 0x68
	s_load_dwordx2 s[8:9], s[0:1], 0x98
	s_waitcnt lgkmcnt(0)
	s_add_u32 s4, s4, 0x5800000
	s_addc_u32 s5, s5, 0
	s_add_u32 s6, s6, 0x2000
	s_addc_u32 s7, s7, 0
	s_add_u32 s8, s8, 0x5200000
	s_addc_u32 s9, s9, 0
	s_sub_u32 s10, s81, 64
	s_add_u32 s10, s10, 2304
	s_mul_hi_u32 s15, s10, 0x1745d18
	s_mul_i32 s14, s15, 176
	s_sub_u32 s14, s10, s14
	s_lshl_b32 s18, s14, 6
	s_mov_b32 s28, 0
	s_mul_i32 s19, s15, 0x160000
	s_add_u32 s19, s19, s18
	s_lshl_b32 s19, s19, 2
	s_add_u32 s20, s4, s19
	s_addc_u32 s21, s5, 0
	s_lshl_b32 s19, s15, 9
	s_add_u32 s22, s6, s19
	s_addc_u32 s23, s7, 0
	global_load_dwordx4 v[12:15], v4, s[20:21]
	global_load_dword v28, v5, s[22:23]
	s_add_u32 s20, s20, 0x160000
	s_addc_u32 s21, s21, 0
	global_load_dwordx4 v[16:19], v4, s[20:21]
	global_load_dword v29, v5, s[22:23] offset:128
	s_add_u32 s20, s20, 0x160000
	s_addc_u32 s21, s21, 0
	global_load_dwordx4 v[20:23], v4, s[20:21]
	global_load_dword v30, v5, s[22:23] offset:256
	s_add_u32 s20, s20, 0x160000
	s_addc_u32 s21, s21, 0
	global_load_dwordx4 v[24:27], v4, s[20:21]
	global_load_dword v31, v5, s[22:23] offset:384
	s_add_u32 s11, s10, 192
	s_cmp_lt_u32 s11, 2816
	s_cbranch_scc0 .Lcv7_p1n
	s_mul_hi_u32 s15, s11, 0x1745d18
	s_mul_i32 s14, s15, 176
	s_sub_u32 s14, s11, s14
	s_lshl_b32 s18, s14, 6
	s_mov_b32 s29, 0
	s_mul_i32 s19, s15, 0x160000
	s_add_u32 s19, s19, s18
	s_lshl_b32 s19, s19, 2
	s_add_u32 s20, s4, s19
	s_addc_u32 s21, s5, 0
	s_lshl_b32 s19, s15, 9
	s_add_u32 s22, s6, s19
	s_addc_u32 s23, s7, 0
	global_load_dwordx4 v[32:35], v4, s[20:21]
	global_load_dword v48, v5, s[22:23]
	s_add_u32 s20, s20, 0x160000
	s_addc_u32 s21, s21, 0
	global_load_dwordx4 v[36:39], v4, s[20:21]
	global_load_dword v49, v5, s[22:23] offset:128
	s_add_u32 s20, s20, 0x160000
	s_addc_u32 s21, s21, 0
	global_load_dwordx4 v[40:43], v4, s[20:21]
	global_load_dword v50, v5, s[22:23] offset:256
	s_add_u32 s20, s20, 0x160000
	s_addc_u32 s21, s21, 0
	global_load_dwordx4 v[44:47], v4, s[20:21]
	global_load_dword v51, v5, s[22:23] offset:384
	s_waitcnt vmcnt(8)
	s_branch .Lcv7_loop

; __device__ __forceinline__ int opaque_tid(int wv) { asm volatile("" : "+s"(wv)); unsigned z = 0u; asm volatile("" : "+v"(z)); const int l = __builtin_amdgcn_mbcnt_hi(~0u, __builtin_amdgcn_mbcnt_lo(~0u, z)); return (wv << 6) | l; }
; __device__ __forceinline__ void convert_weight(int wv, const float* __restrict__ src, int ldsrc, int Ksrc, bf16_t* dst, int ldd, int koff, int ntn, const float* kscale, int mode, LAS float* tile, int pidx, int pcnt) {
;     const int tid = opaque_tid(wv); const int ntk = Ksrc / 128; const int total = ntn * ntk; const int G = pcnt;
;     const int kk0 = tid >> 4, n4 = (tid & 15) * 4;
;     f32x4 v[4]; float ks[4];
;     auto prefetch = [&](int t) {
;         const int tn = t % ntn, tk = t / ntn; const int n0 = tn * 64, k0 = tk * 128;
;         int scol = n0, nvalid = 64;
;         if (mode == 1) { if (n0 < 5632) scol = n0; else if (n0 < 13312) scol = n0 + 8; else if (n0 == 13312) { scol = 5632; nvalid = 8; } else { scol = 0; nvalid = 0; } }
; #pragma unroll
;         for (int i = 0; i < 4; ++i) { const int kk = kk0 + i * 32; v[i] = (f32x4){0.f, 0.f, 0.f, 0.f};
;             if (n4 < nvalid) v[i] = *(const f32x4*)(src + (size_t)(k0 + kk) * ldsrc + scol + n4);
;             ks[i] = kscale ? kscale[k0 + kk] : 1.0f; }
;     };
;     int t = pidx; int buf = 0;
;     if (t < total) prefetch(t);
; __device__ __forceinline__ void convert_layer(int wv, PP P, int L, int mask, LAS float* tile, int pidx, int pcnt) {
;     ...
;     if (mask & 1) convert_weight(wv, P->w_in + (size_t)L * D * DIN, DIN, D, (bf16_t*)(ws + WS_WIN), D, 0, NZ / 64, P->norm_mix + L * D, 1, tile, pidx, pcnt);
.LBB0_945:
	v_readlane_b32 s4, v254, 30
	v_readlane_b32 s5, v254, 31
	s_and_b64 vcc, exec, s[4:5]
	s_cbranch_vccnz .LBB0_970
	s_mov_b32 s4, s81
	s_movk_i32 s5, 64
	s_cmp_lt_i32 s4, s5
	s_cselect_b64 s[6:7], -1, 0
	s_or_b64 s[6:7], s[82:83], s[6:7]
	s_and_b64 vcc, exec, s[6:7]
	s_cbranch_vccnz .LBB0_970
	s_movk_i32 s5, 64
	s_sub_i32 s16, s4, s5
	s_mov_b64 s[10:11], s[0:1]
	s_mov_b32 s4, s95
	v_mov_b32_e32 v0, v3
	s_cmpk_gt_i32 s16, 0xaff
	s_cbranch_scc1 .LBB0_969
	v_mbcnt_lo_u32_b32 v10, -1, 0
	v_mbcnt_hi_u32_b32 v10, -1, v10
	v_lshl_or_b32 v10, s95, 6, v10
	v_lshrrev_b32_e32 v11, 4, v10
	v_and_b32_e32 v9, 15, v10
	v_lshlrev_b32_e32 v9, 2, v9
	v_mul_u32_u24_e32 v4, 0x3408, v11
	v_add_u32_e32 v4, v4, v9
	v_lshlrev_b32_e32 v4, 2, v4
	v_lshlrev_b32_e32 v5, 2, v11
	v_mul_u32_u24_e32 v6, 65, v11
	v_add_u32_e32 v6, v6, v9
	v_lshlrev_b32_e32 v6, 2, v6
	v_lshrrev_b32_e32 v7, 3, v10
	v_and_b32_e32 v8, 7, v10
	v_lshlrev_b32_e32 v8, 4, v8
	v_mul_u32_u24_e32 v11, 65, v8
	v_add_u32_e32 v11, v11, v7
	v_lshlrev_b32_e32 v8, 1, v8
	v_mul_u32_u24_e32 v10, 0x1000, v7
	v_add_u32_e32 v8, v10, v8
	v_lshlrev_b32_e32 v7, 2, v11
	s_load_dwordx2 s[4:5], s[0:1], 0x18
	s_load_dwordx2 s[6:7], s[0:1], 0x10
	s_load_dwordx2 s[8:9], s[0:1], 0xa0
	s_waitcnt lgkmcnt(0)
	s_add_u32 s4, s4, 0x6810000
	s_addc_u32 s5, s5, 0
	s_add_u32 s6, s6, 0x2000
	s_addc_u32 s7, s7, 0
	s_add_u32 s8, s8, 0x23100000
	s_addc_u32 s9, s9, 0
	s_mov_b32 s10, s16
	s_mul_hi_u32 s15, s10, 0x13521d0
	s_mul_i32 s14, s15, 212
	s_sub_u32 s14, s10, s14
	s_lshl_b32 s18, s14, 6
	s_mov_b32 s28, 0
	s_cmp_lt_u32 s14, 88
	s_cbranch_scc1 .Lcv2_cp0
	s_add_u32 s18, s18, 8
	s_cmp_lt_u32 s14, 208
	s_cbranch_scc1 .Lcv2_cp0
	s_movk_i32 s18, 0x1600
	s_mov_b32 s28, 1
	s_cmp_eq_u32 s14, 208
	s_cbranch_scc1 .Lcv2_cp0
	s_mov_b32 s18, 0
	s_mov_b32 s28, 2
